# attention loop back-edge rotation: counter/exit test/K-address setup moved in front of the loop barrier, barrier becomes the loop head
# speedup vs baseline: 1.0659x; 1.0082x over previous
; template <bool DIFF> ...
;     ...
;     bf16x8 bq[KS];
; #pragma unroll
;     for (int f = 0; f < KS; ++f) bq[f] = *(const bf16x8*)(qrow + mp * 64 + f * 16 + h * 8);
;     float m_ = -INFINITY; f32x16 O[4], lacc;
;     const bf16x8 ones = {0x3F80, 0x3F80, 0x3F80, 0x3F80, 0x3F80, 0x3F80, 0x3F80, 0x3F80};
; #pragma unroll
;     for (int ii = 0; ii < 16; ++ii) lacc[ii] = 0.f;
; #pragma unroll
;     for (int db = 0; db < 4; ++db)
; #pragma unroll
;         for (int ii = 0; ii < 16; ++ii) O[db][ii] = 0.f;
;     int goff[5];
; #pragma unroll
;     for (int i = 0; i < 5; ++i) { int op = wave + 8 * i; op = op > 36 ? 36 : op; const bool isk = op < 17; const int slot = (isk ? op : op - 17) * 64 + lane; const int per = isk ? 17 : 20;
;         const int row = slot / per; int pcs = slot - row * per; pcs = pcs > 15 ? 15 : pcs; goff[i] = (row << 10) | (pcs << 4); }
.LBB0_1479:
	v_readfirstlane_b32 s42, v2
	v_readfirstlane_b32 s43, v3
	v_readfirstlane_b32 s40, v4
	v_readfirstlane_b32 s41, v5
	v_readfirstlane_b32 s89, v176
	s_lshr_b32 s86, s89, 6
	s_bfe_u32 s87, s89, 0x10006
	s_lshl_b32 s94, s87, 7
	s_min_u32 s0, s86, 36
	s_cmpk_lt_u32 s89, 0x440
	s_cselect_b64 s[6:7], -1, 0
	s_lshl_b32 s1, s0, 6
	s_add_i32 s8, s1, 0xfffffbc0
	s_and_b64 s[4:5], s[6:7], exec
	v_lshl_add_u64 v[6:7], v[6:7], 0, s[94:95]
	v_lshlrev_b32_e32 v0, 1, v144
	s_cselect_b32 s1, s1, s8
	s_cselect_b32 s4, 17, 20
	v_lshl_add_u64 v[6:7], v[6:7], 0, v[0:1]
	v_or_b32_e32 v0, s1, v206
	v_cvt_f32_ubyte0_e32 v10, s4
	v_cvt_f32_i32_e32 v8, v0
	v_rcp_iflag_f32_e32 v11, v10
	global_load_dwordx4 v[128:131], v[6:7], off
	global_load_dwordx4 v[132:135], v[6:7], off offset:32
	global_load_dwordx4 v[136:139], v[6:7], off offset:64
	global_load_dwordx4 v[140:143], v[6:7], off offset:96
	s_ashr_i32 s1, s1, 30
	v_mul_f32_e32 v6, v8, v11
	v_trunc_f32_e32 v6, v6
	s_or_b32 s1, s1, 1
	v_fma_f32 v7, -v6, v10, v8
	v_cvt_i32_f32_e32 v6, v6
	v_mov_b32_e32 v8, s1
	s_min_u32 s1, s86, 28
	v_cmp_ge_f32_e64 vcc, |v7|, v10
	s_add_i32 s12, s1, 8
	s_cmpk_lt_u32 s89, 0x240
	v_cndmask_b32_e32 v7, 0, v8, vcc
	v_add_u32_e32 v6, v6, v7
	s_cselect_b64 s[8:9], -1, 0
	s_lshl_b32 s1, s12, 6
	v_bfe_i32 v6, v6, 0, 14
	s_add_i32 s10, s1, 0xfffffbc0
	v_mul_i32_i24_e32 v7, s4, v6
	s_and_b64 s[4:5], s[8:9], exec
	s_cselect_b32 s1, s1, s10
	s_cselect_b32 s4, 17, 20
	v_or_b32_e32 v8, s1, v206
	v_cvt_f32_ubyte0_e32 v11, s4
	v_cvt_f32_i32_e32 v10, v8
	v_rcp_iflag_f32_e32 v12, v11
	s_ashr_i32 s1, s1, 30
	s_or_b32 s1, s1, 1
	v_mov_b32_e32 v13, s1
	v_mul_f32_e32 v12, v10, v12
	v_trunc_f32_e32 v12, v12
	v_fma_f32 v10, -v12, v11, v10
	v_cvt_i32_f32_e32 v12, v12
	v_cmp_ge_f32_e64 vcc, |v10|, v11
	s_min_u32 s1, s86, 20
	s_add_i32 s13, s1, 16
	v_cndmask_b32_e32 v10, 0, v13, vcc
	v_add_u32_e32 v10, v12, v10
	s_cmp_lt_u32 s89, 64
	v_bfe_i32 v10, v10, 0, 14
	s_cselect_b64 s[10:11], -1, 0
	s_lshl_b32 s1, s13, 6
	v_mul_i32_i24_e32 v11, s4, v10
	s_addk_i32 s1, 0xfbc0
	v_sub_u32_e32 v8, v8, v11
	s_and_b64 s[4:5], s[10:11], exec
	v_min_i32_e32 v8, 15, v8
	s_cselect_b32 s1, 0x400, s1
	s_cselect_b32 s4, 17, 20
	v_lshlrev_b32_e32 v12, 4, v8
	v_or_b32_e32 v8, s1, v206
	v_cvt_f32_ubyte0_e32 v13, s4
	v_cvt_f32_i32_e32 v11, v8
	v_rcp_iflag_f32_e32 v14, v13
	v_lshl_or_b32 v15, v10, 10, v12
	s_ashr_i32 s1, s1, 30
	s_or_b32 s1, s1, 1
	v_mul_f32_e32 v10, v11, v14
	v_trunc_f32_e32 v10, v10
	v_fma_f32 v11, -v10, v13, v11
	v_cvt_i32_f32_e32 v10, v10
	v_mov_b32_e32 v14, s1
	v_cmp_ge_f32_e64 vcc, |v11|, v13
	s_min_u32 s1, s86, 12
	s_movk_i32 s14, 0xffec
	v_cndmask_b32_e32 v11, 0, v14, vcc
	v_add_u32_e32 v10, v10, v11
	v_bfe_i32 v10, v10, 0, 14
	v_mul_i32_i24_e32 v11, s4, v10
	v_sub_u32_e32 v8, v8, v11
	v_min_i32_e32 v8, 15, v8
	s_add_i32 s4, s1, 24
	v_lshlrev_b32_e32 v14, 4, v8
	v_lshl_add_u32 v8, s4, 6, v145
	v_lshl_or_b32 v16, v10, 10, v14
	v_mul_u32_u24_e32 v10, 0xcccd, v8
	v_lshrrev_b32_e32 v11, 20, v10
	v_mad_i32_i24 v8, v11, s14, v8
	s_min_u32 s1, s86, 4
	v_min_i32_e32 v8, 15, v8
	s_or_b32 s5, s1, 32
	v_lshrrev_b32_e32 v10, 10, v10
	v_lshlrev_b32_e32 v17, 4, v8
	v_lshl_add_u32 v8, s5, 6, v145
	v_sub_u32_e32 v0, v0, v7
	v_or_b32_e32 v18, v17, v10
	v_mul_u32_u24_e32 v10, 0xcccd, v8
	v_min_i32_e32 v0, 15, v0
	v_lshrrev_b32_e32 v11, 20, v10
	v_lshlrev_b32_e32 v0, 4, v0
	v_mad_i32_i24 v8, v11, s14, v8
	v_lshl_or_b32 v6, v6, 10, v0
	v_min_i32_e32 v8, 15, v8
	v_lshrrev_b32_e32 v10, 10, v10
	v_lshlrev_b32_e32 v19, 4, v8
	s_add_i32 s83, s81, -1
	v_ashrrev_i32_e32 v21, 10, v6
	v_or_b32_e32 v20, v19, v10
	v_min_i32_e32 v10, s83, v21
	s_lshl_b32 s14, s0, 10
	v_ashrrev_i32_e32 v11, 31, v10
	s_add_i32 s15, s14, 0x8800
	v_cndmask_b32_e64 v9, v3, v5, s[6:7]
	v_cndmask_b32_e64 v8, v2, v4, s[6:7]
	v_lshlrev_b64 v[10:11], 10, v[10:11]
	s_and_b64 s[0:1], s[6:7], exec
	v_lshl_add_u64 v[10:11], v[8:9], 0, v[10:11]
	v_and_b32_e32 v0, 0x3f0, v0
	s_cselect_b32 s0, s14, s15
	s_barrier
; #define LAS __attribute__((address_space(3)))
; #define A_WAITBAR(N) asm volatile("s_waitcnt vmcnt(" #N ") lgkmcnt(0)\n\ts_barrier" ::: "memory")
; template <bool DIFF> ...
;     ...
;     float m_ = -INFINITY; f32x16 O[4], lacc;
;     const bf16x8 ones = {0x3F80, 0x3F80, 0x3F80, 0x3F80, 0x3F80, 0x3F80, 0x3F80, 0x3F80};
; #pragma unroll
;     for (int ii = 0; ii < 16; ++ii) lacc[ii] = 0.f;
; #pragma unroll
;     for (int db = 0; db < 4; ++db)
; #pragma unroll
;         for (int ii = 0; ii < 16; ++ii) O[db][ii] = 0.f;
;     int goff[5];
; #pragma unroll
;     for (int i = 0; i < 5; ++i) { int op = wave + 8 * i; op = op > 36 ? 36 : op; const bool isk = op < 17; const int slot = (isk ? op : op - 17) * 64 + lane; const int per = isk ? 17 : 20;
;         const int row = slot / per; int pcs = slot - row * per; pcs = pcs > 15 ? 15 : pcs; goff[i] = (row << 10) | (pcs << 4); }
;     ...
;     __syncthreads();
;     asm volatile("s_waitcnt vmcnt(0)" ::: "memory");
;     A_DMA(0, 0, 0);
;     A_WAITBAR(0);
;     const int q4 = (lane & 15) >> 2, p4 = lane & 3, g1 = (lane >> 4) & 1;
;     const LAS unsigned char* vb0 = lds + A_VB + (4 * h + q4) * A_VSTR + 32 * g1 + 8 * p4;
;     ...
;     const bool late = false;
;     bool first = true, pact = false;
;     bf16x8 pk[2][2];
;     int k3 = 0;
;     for (int t = 0; t < NT; ++t) {
;         const int k3n = (k3 == 2) ? 0 : k3 + 1;
	s_waitcnt vmcnt(0)
	v_lshl_add_u64 v[10:11], v[10:11], 0, v[0:1]
	s_add_i32 m0, s0, 0
	v_ashrrev_i32_e32 v22, 10, v15
	global_load_lds_dwordx4 v[10:11], off
	v_min_i32_e32 v10, s83, v22
	s_lshl_b32 s12, s12, 10
	v_ashrrev_i32_e32 v11, 31, v10
	s_add_i32 s15, s12, 0x8800
	v_cndmask_b32_e64 v7, v3, v5, s[8:9]
	v_cndmask_b32_e64 v6, v2, v4, s[8:9]
	v_lshlrev_b64 v[10:11], 10, v[10:11]
	s_and_b64 s[0:1], s[8:9], exec
	v_lshl_add_u64 v[10:11], v[6:7], 0, v[10:11]
	v_and_b32_e32 v12, 0x3f0, v12
	v_mov_b32_e32 v13, v1
	s_cselect_b32 s0, s12, s15
	v_lshl_add_u64 v[10:11], v[10:11], 0, v[12:13]
	s_add_i32 m0, s0, 0
	v_ashrrev_i32_e32 v23, 10, v16
	global_load_lds_dwordx4 v[10:11], off
	v_min_i32_e32 v10, s83, v23
	s_lshl_b32 s13, s13, 10
	v_ashrrev_i32_e32 v11, 31, v10
	s_add_i32 s15, s13, 0x8800
	v_cndmask_b32_e64 v5, v3, v5, s[10:11]
	v_cndmask_b32_e64 v4, v2, v4, s[10:11]
	v_lshlrev_b64 v[10:11], 10, v[10:11]
	s_and_b64 s[0:1], s[10:11], exec
	v_lshl_add_u64 v[10:11], v[4:5], 0, v[10:11]
	v_and_b32_e32 v14, 0x3f0, v14
	v_mov_b32_e32 v15, v1
	s_cselect_b32 s0, 0x4000, s15
	v_lshl_add_u64 v[10:11], v[10:11], 0, v[14:15]
	s_add_i32 m0, s0, 0
	v_ashrrev_i32_e32 v24, 10, v18
	global_load_lds_dwordx4 v[10:11], off
	v_min_i32_e32 v10, s83, v24
	v_ashrrev_i32_e32 v11, 31, v10
	v_lshlrev_b64 v[10:11], 10, v[10:11]
	s_lshl_b32 s0, s4, 10
	v_lshl_add_u64 v[10:11], v[2:3], 0, v[10:11]
	v_and_b32_e32 v16, 0x3f0, v17
	v_mov_b32_e32 v17, v1
	s_add_i32 s4, s0, 0
	v_lshl_add_u64 v[10:11], v[10:11], 0, v[16:17]
	s_add_i32 m0, s4, 0x8800
	v_ashrrev_i32_e32 v20, 10, v20
	global_load_lds_dwordx4 v[10:11], off
	v_min_i32_e32 v10, s83, v20
	v_ashrrev_i32_e32 v11, 31, v10
	v_lshlrev_b64 v[10:11], 10, v[10:11]
	s_lshl_b32 s0, s5, 10
	v_lshl_add_u64 v[10:11], v[2:3], 0, v[10:11]
	v_and_b32_e32 v18, 0x3f0, v19
	v_mov_b32_e32 v19, v1
	s_add_i32 s5, s0, 0
	v_lshl_add_u64 v[10:11], v[10:11], 0, v[18:19]
	s_add_i32 m0, s5, 0x8800
	v_mov_b32_e32 v178, v14
	global_load_lds_dwordx4 v[10:11], off
	s_waitcnt vmcnt(0) lgkmcnt(0)
	s_barrier
	v_mov_b32_e32 v14, v1
	v_mov_b32_e32 v172, v0
	v_mov_b32_e32 v174, v12
	v_mov_b32_e32 v180, v16
	v_mov_b32_e32 v182, v18
	v_add_u32_e32 v155, 64, v20
	v_add_u32_e32 v157, 64, v24
	v_add_u32_e32 v159, 64, v23
	v_add_u32_e32 v161, 64, v22
	v_add_u32_e32 v163, 64, v21
	v_mov_b32_e32 v0, v1
	v_mov_b32_e32 v2, v1
	v_mov_b32_e32 v3, v1
	v_mov_b32_e32 v4, v1
	v_mov_b32_e32 v5, v1
	v_mov_b32_e32 v6, v1
	v_mov_b32_e32 v7, v1
	v_mov_b32_e32 v8, v1
	v_mov_b32_e32 v9, v1
	v_mov_b32_e32 v10, v1
	v_mov_b32_e32 v11, v1
	v_mov_b32_e32 v12, v1
	v_mov_b64_e32 v[46:47], v[14:15]
	v_mov_b64_e32 v[30:31], v[14:15]
	v_mov_b64_e32 v[62:63], v[14:15]
	v_mov_b64_e32 v[78:79], v[14:15]
	v_mov_b64_e32 v[94:95], v[14:15]
	s_mov_b32 s0, 0
	s_lshr_b32 s88, s89, 7
	s_sub_i32 s1, s81, 64
	s_add_i32 s90, s14, 0
	s_add_i32 s92, s12, 0
	s_add_i32 s93, s13, 0
	v_add_u32_e32 v148, s94, v208
	s_mov_b64 s[12:13], -1
	v_mov_b32_e32 v153, 0xff800000
	v_mov_b64_e32 v[44:45], v[12:13]
	v_mov_b64_e32 v[42:43], v[10:11]
	v_mov_b64_e32 v[40:41], v[8:9]
	v_mov_b64_e32 v[38:39], v[6:7]
	v_mov_b64_e32 v[36:37], v[4:5]
	v_mov_b64_e32 v[34:35], v[2:3]
	v_mov_b64_e32 v[32:33], v[0:1]
	v_mov_b64_e32 v[28:29], v[12:13]
	v_mov_b64_e32 v[26:27], v[10:11]
	v_mov_b64_e32 v[24:25], v[8:9]
	v_mov_b64_e32 v[22:23], v[6:7]
	v_mov_b64_e32 v[20:21], v[4:5]
	v_mov_b64_e32 v[18:19], v[2:3]
	v_mov_b64_e32 v[16:17], v[0:1]
	v_mov_b64_e32 v[60:61], v[12:13]
	v_mov_b64_e32 v[58:59], v[10:11]
	v_mov_b64_e32 v[56:57], v[8:9]
	v_mov_b64_e32 v[54:55], v[6:7]
	v_mov_b64_e32 v[52:53], v[4:5]
	v_mov_b64_e32 v[50:51], v[2:3]
	v_mov_b64_e32 v[48:49], v[0:1]
	v_mov_b64_e32 v[76:77], v[12:13]
	v_mov_b64_e32 v[74:75], v[10:11]
	v_mov_b64_e32 v[72:73], v[8:9]
	v_mov_b64_e32 v[70:71], v[6:7]
	v_mov_b64_e32 v[68:69], v[4:5]
	v_mov_b64_e32 v[66:67], v[2:3]
	v_mov_b64_e32 v[64:65], v[0:1]
	v_mov_b64_e32 v[92:93], v[12:13]
	v_mov_b64_e32 v[90:91], v[10:11]
	v_mov_b64_e32 v[88:89], v[8:9]
	v_mov_b64_e32 v[86:87], v[6:7]
	v_mov_b64_e32 v[84:85], v[4:5]
	v_mov_b64_e32 v[82:83], v[2:3]
	v_mov_b64_e32 v[80:81], v[0:1]
	s_mov_b32 s14, 0
	s_mov_b32 s15, 0
	s_waitcnt vmcnt(0)
	s_and_b64 s[16:17], s[6:7], exec
	s_cselect_b64 s[44:45], s[40:41], s[42:43]
	s_and_b64 s[16:17], s[8:9], exec
	s_cselect_b64 s[46:47], s[40:41], s[42:43]
	s_and_b64 s[16:17], s[10:11], exec
	s_cselect_b64 s[48:49], s[40:41], s[42:43]
	v_mov_b32_e32 v240, 0
	v_mov_b32_e32 v241, 0
	v_mov_b32_e32 v242, 0
	v_mov_b32_e32 v243, 0
	s_add_i32 s16, s14, 1
	s_cmp_lg_u32 s14, 2
	s_cselect_b32 s84, s16, 0
	s_mul_i32 s16, s14, 0x4400
	v_add_u32_e32 v0, s16, v148
	s_branch .Lattn_head_nobar

; #define LAS __attribute__((address_space(3)))
; #define MFMA32(a, b, c) __builtin_amdgcn_mfma_f32_32x32x16_bf16((a), (b), (c), 0, 0, 0)
; template <bool DIFF> ...
;     ...
;     for (int t = 0; t < NT; ++t) {
;         const int k3n = (k3 == 2) ? 0 : k3 + 1;
;         if (t + 1 < NT) A_DMA(t + 1, k3n, (t + 1) & 3);
;         if (late && pact) A_PV((t - 1) & 3);
;         const bool active = split ? ((t % NG) == grp) : (t <= my_lim);
;         if (active) {
;             const LAS unsigned char* kbuf = lds + A_KB + k3 * 17408 + mp * 128;
;             const float cin = first ? 0.f : -m_;
;             f32x16 s0, s1;
; #pragma unroll
;             for (int ii = 0; ii < 16; ++ii) { s0[ii] = cin; s1[ii] = cin; }
; #pragma unroll
;             for (int ks = 0; ks < KS; ++ks) {
;                 const bf16x8 a0 = *(const LAS bf16x8*)(kbuf + r * 272 + (ks * 16 + h * 8) * 2);
;                 const bf16x8 a1 = *(const LAS bf16x8*)(kbuf + (32 + r) * 272 + (ks * 16 + h * 8) * 2);
;                 s0 = MFMA32(a0, bq[ks], s0); s1 = MFMA32(a1, bq[ks], s1);
.Lattn_head_nobar:
	ds_read_b128 v[2:5], v0
	ds_read_b128 v[10:13], v0 offset:8704
	ds_read_b128 v[6:9], v0 offset:32
	ds_read_b128 v[212:215], v0 offset:8736
	ds_read_b128 v[216:219], v0 offset:64
	ds_read_b128 v[224:227], v0 offset:8768
	ds_read_b128 v[220:223], v0 offset:96
	ds_read_b128 v[228:231], v0 offset:8800
	s_add_i32 s85, s15, 1
	s_cmp_ge_u32 s85, s80
	s_cbranch_scc1 .LBB0_1482
	s_and_b32 s16, s85, 3
	s_mulk_i32 s16, 0x5000
	s_add_i32 s18, s16, 0x8800
	s_mul_i32 s19, s84, 0x4400
	v_add_u32_e32 v0, s0, v163
	v_add_u32_e32 v14, s0, v161
	v_min_i32_e32 v0, s83, v0
	v_min_i32_e32 v14, s83, v14
	v_lshl_add_u32 v0, v0, 10, v172
	v_lshl_add_u32 v14, v14, 10, v174
	s_and_b64 s[16:17], s[6:7], exec
	s_cselect_b32 s16, s19, s18
	s_add_i32 m0, s90, s16
	s_nop 0
	global_load_lds_dwordx4 v0, s[44:45]
	s_and_b64 s[16:17], s[8:9], exec
	s_cselect_b32 s16, s19, s18
	s_add_i32 m0, s92, s16
	v_add_u32_e32 v15, s0, v159
	global_load_lds_dwordx4 v14, s[46:47]
	v_min_i32_e32 v15, s83, v15
	v_lshl_add_u32 v15, v15, 10, v178
	s_and_b64 s[16:17], s[10:11], exec
	s_cselect_b32 s16, s19, s18
	s_add_i32 m0, s93, s16
	v_add_u32_e32 v0, s0, v157
	global_load_lds_dwordx4 v15, s[48:49]
	v_min_i32_e32 v0, s83, v0
	v_lshl_add_u32 v0, v0, 10, v180
	s_add_i32 m0, s18, s4
	v_add_u32_e32 v14, s0, v155
	global_load_lds_dwordx4 v0, s[42:43]
	v_min_i32_e32 v14, s83, v14
	v_lshl_add_u32 v14, v14, 10, v182
	s_add_i32 m0, s18, s5
	s_nop 0
	global_load_lds_dwordx4 v14, s[42:43]

; #define A_WAITBAR(N) asm volatile("s_waitcnt vmcnt(" #N ") lgkmcnt(0)\n\ts_barrier" ::: "memory")
; template <bool DIFF> ...
;     ...
;         pact = active; k3 = k3n;
;         A_WAITBAR(0);
;     }
;     ...
;     float l_ = lacc[0];
;     bool have = true;
;     if (split) {
;         if (h == 0) mb[wave * 32 + r] = m_;
;         __syncthreads();
;         float M = mb[mp * 32 + r];
; #pragma unroll
;         for (int g = 1; g < NG; ++g) M = fmaxf(M, mb[(g * NM + mp) * 32 + r]);
;         const float f = __builtin_amdgcn_exp2f(m_ - M);
;         l_ *= f;
;         if (h == 0) lb[wave * 32 + r] = l_;
; #pragma unroll
;         for (int db = 0; db < 4; ++db)
; #pragma unroll
;             for (int ii = 0; ii < 16; ++ii) red[(wave * 64 + db * 16 + ii) * 64 + lane] = O[db][ii] * f;
.LBB0_1493:
.LBB0_1495:
	s_add_i32 s0, s0, 64
	s_cmp_eq_u32 s80, s85
	s_cbranch_scc1 .Lattn_exit
	s_mov_b32 s14, s84
	s_mov_b32 s15, s85
	s_add_i32 s16, s14, 1
	s_cmp_lg_u32 s14, 2
	s_cselect_b32 s84, s16, 0
	s_mul_i32 s16, s14, 0x4400
	v_add_u32_e32 v0, s16, v148
	s_branch .LBB0_1480
.LBB0_1497:
	s_mov_b64 s[14:15], 0
	s_cbranch_execnz .LBB0_1489
	s_branch .LBB0_1490
.Lattn_exit:
	s_waitcnt vmcnt(0) lgkmcnt(0)
	s_barrier
.LBB0_1498:
	v_add_f32_e32 v80, v240, v241
	v_add_f32_e32 v82, v242, v243
	v_add_f32_e32 v80, v80, v82
	v_mov_b32_e32 v81, v80
	s_nop 1
	v_permlane32_swap_b32_e32 v80, v81
	v_add_f32_e32 v80, v80, v81
	s_mov_b64 s[6:7], -1
	s_and_b64 vcc, exec, s[2:3]
	s_waitcnt vmcnt(0) lgkmcnt(0)
	s_barrier
	s_cbranch_vccz .LBB0_1506
	s_mov_b64 s[2:3], exec
	v_readlane_b32 s0, v255, 5
	v_readlane_b32 s1, v255, 6
	v_readlane_b32 s40, v255, 19
	v_readlane_b32 s20, v255, 21
	s_and_b64 s[0:1], s[2:3], s[0:1]
	v_readlane_b32 s41, v255, 20
	v_readlane_b32 s21, v255, 22
	v_readlane_b32 s14, v255, 23
	s_mov_b64 exec, s[0:1]
	v_lshl_add_u32 v0, s86, 7, v186
	ds_write_b32 v0, v153
	s_or_b64 exec, exec, s[2:3]
	v_add_u32_e32 v0, s94, v186
	s_waitcnt lgkmcnt(0)
	s_barrier
	ds_read2st64_b32 v[2:3], v0 offset1:1
	ds_read2st64_b32 v[4:5], v0 offset0:2 offset1:3
	s_waitcnt lgkmcnt(1)
	v_max_f32_e32 v0, v3, v3
	v_max_f32_e32 v2, v2, v2
	v_max_f32_e32 v0, v2, v0
	s_waitcnt lgkmcnt(0)
	v_max3_f32 v0, v0, v4, v5
	v_sub_f32_e32 v0, v153, v0
	v_exp_f32_e32 v2, v0
	v_lshl_add_u32 v0, s86, 7, v187
	v_mul_f32_e32 v80, v80, v2
	s_mov_b64 s[2:3], exec
	v_readlane_b32 s0, v255, 5
	v_readlane_b32 s1, v255, 6
	s_and_b64 s[0:1], s[2:3], s[0:1]
	s_mov_b64 exec, s[0:1]
	ds_write_b32 v0, v80
	s_or_b64 exec, exec, s[2:3]
	s_lshl_b32 s0, s89, 8
	s_and_b32 s1, s0, 0xffffc000
	v_mul_f32_e32 v3, v32, v2
	v_add_u32_e32 v4, s1, v184
	v_mul_f32_e32 v5, v33, v2
	ds_write2st64_b32 v4, v3, v5 offset1:1
	v_mul_f32_e32 v3, v34, v2
	v_mul_f32_e32 v5, v35, v2
	ds_write2st64_b32 v4, v3, v5 offset0:2 offset1:3
	v_mul_f32_e32 v3, v36, v2
	v_mul_f32_e32 v5, v37, v2
	ds_write2st64_b32 v4, v3, v5 offset0:4 offset1:5
	v_mul_f32_e32 v3, v38, v2
	v_mul_f32_e32 v5, v39, v2
	ds_write2st64_b32 v4, v3, v5 offset0:6 offset1:7
	v_mul_f32_e32 v3, v40, v2
	v_mul_f32_e32 v5, v41, v2
	ds_write2st64_b32 v4, v3, v5 offset0:8 offset1:9
	v_mul_f32_e32 v3, v42, v2
	v_mul_f32_e32 v5, v43, v2
	ds_write2st64_b32 v4, v3, v5 offset0:10 offset1:11
	v_mul_f32_e32 v3, v44, v2
	v_mul_f32_e32 v5, v45, v2
	ds_write2st64_b32 v4, v3, v5 offset0:12 offset1:13
	v_mul_f32_e32 v3, v46, v2
	v_mul_f32_e32 v5, v47, v2
	ds_write2st64_b32 v4, v3, v5 offset0:14 offset1:15
	v_mul_f32_e32 v3, v16, v2
	v_mul_f32_e32 v5, v17, v2
	ds_write2st64_b32 v4, v3, v5 offset0:16 offset1:17
	v_mul_f32_e32 v3, v18, v2
	v_mul_f32_e32 v5, v19, v2
	ds_write2st64_b32 v4, v3, v5 offset0:18 offset1:19
	v_mul_f32_e32 v3, v20, v2
	v_mul_f32_e32 v5, v21, v2
	ds_write2st64_b32 v4, v3, v5 offset0:20 offset1:21
	v_mul_f32_e32 v3, v22, v2
	v_mul_f32_e32 v5, v23, v2
	ds_write2st64_b32 v4, v3, v5 offset0:22 offset1:23
	v_mul_f32_e32 v3, v24, v2
	v_mul_f32_e32 v5, v25, v2
	ds_write2st64_b32 v4, v3, v5 offset0:24 offset1:25
	v_mul_f32_e32 v3, v26, v2
	v_mul_f32_e32 v5, v27, v2
	ds_write2st64_b32 v4, v3, v5 offset0:26 offset1:27
	v_mul_f32_e32 v3, v28, v2
	v_mul_f32_e32 v5, v29, v2
	ds_write2st64_b32 v4, v3, v5 offset0:28 offset1:29
	v_mul_f32_e32 v3, v30, v2
	v_mul_f32_e32 v5, v31, v2
	ds_write2st64_b32 v4, v3, v5 offset0:30 offset1:31
	v_mul_f32_e32 v3, v48, v2
	v_mul_f32_e32 v5, v49, v2
	ds_write2st64_b32 v4, v3, v5 offset0:32 offset1:33
	v_mul_f32_e32 v3, v50, v2
	v_mul_f32_e32 v5, v51, v2
	ds_write2st64_b32 v4, v3, v5 offset0:34 offset1:35
	v_mul_f32_e32 v3, v52, v2
	v_mul_f32_e32 v5, v53, v2
	ds_write2st64_b32 v4, v3, v5 offset0:36 offset1:37
	v_mul_f32_e32 v3, v54, v2
	v_mul_f32_e32 v5, v55, v2
	ds_write2st64_b32 v4, v3, v5 offset0:38 offset1:39
	v_mul_f32_e32 v3, v56, v2
	v_mul_f32_e32 v5, v57, v2
	ds_write2st64_b32 v4, v3, v5 offset0:40 offset1:41
	v_mul_f32_e32 v3, v58, v2
	v_mul_f32_e32 v5, v59, v2
	ds_write2st64_b32 v4, v3, v5 offset0:42 offset1:43
	v_mul_f32_e32 v3, v60, v2
	v_mul_f32_e32 v5, v61, v2
	ds_write2st64_b32 v4, v3, v5 offset0:44 offset1:45
	v_mul_f32_e32 v3, v62, v2
	v_mul_f32_e32 v5, v63, v2
	ds_write2st64_b32 v4, v3, v5 offset0:46 offset1:47
	v_mul_f32_e32 v3, v64, v2
	v_mul_f32_e32 v5, v65, v2
	ds_write2st64_b32 v4, v3, v5 offset0:48 offset1:49
	v_mul_f32_e32 v3, v66, v2
	v_mul_f32_e32 v5, v67, v2
	ds_write2st64_b32 v4, v3, v5 offset0:50 offset1:51
	v_mul_f32_e32 v3, v68, v2
	v_mul_f32_e32 v5, v69, v2
	ds_write2st64_b32 v4, v3, v5 offset0:52 offset1:53
	v_mul_f32_e32 v3, v70, v2
	v_mul_f32_e32 v5, v71, v2
	ds_write2st64_b32 v4, v3, v5 offset0:54 offset1:55
	v_mul_f32_e32 v3, v72, v2
	v_mul_f32_e32 v5, v73, v2
	ds_write2st64_b32 v4, v3, v5 offset0:56 offset1:57
	v_mul_f32_e32 v3, v74, v2
	v_mul_f32_e32 v5, v75, v2
	ds_write2st64_b32 v4, v3, v5 offset0:58 offset1:59
	v_mul_f32_e32 v3, v76, v2
	v_mul_f32_e32 v5, v77, v2
	s_cmpk_lt_u32 s89, 0x80
	ds_write2st64_b32 v4, v3, v5 offset0:60 offset1:61
	v_mul_f32_e32 v3, v78, v2
	v_mul_f32_e32 v2, v79, v2
	s_cselect_b64 s[6:7], -1, 0
	s_cmpk_gt_u32 s89, 0x7f
	ds_write2st64_b32 v4, v3, v2 offset0:62 offset1:63
	s_waitcnt lgkmcnt(0)
	s_barrier
	s_cbranch_scc1 .LBB0_1505
; template <bool DIFF> ...
;     ...
;         have = wave < NM;
;         if (have) {
; #pragma unroll
;             for (int db = 0; db < 4; ++db)
; #pragma unroll
;                 for (int ii = 0; ii < 16; ++ii) { float a = 0.f;
; #pragma unroll
;                     for (int g = 0; g < NG; ++g) a += red[((g * NM + mp) * 64 + db * 16 + ii) * 64 + lane];
;                     O[db][ii] = a; }
	s_and_b32 s1, s0, 0x4000
	s_or_b32 s2, s1, 0x100
	v_add_u32_e32 v8, s2, v188
	v_add_u32_e32 v9, s2, v189
	s_or_b32 s2, s1, 0x200
	v_add_u32_e32 v12, s2, v188
	v_add_u32_e32 v13, s2, v189
	s_or_b32 s2, s1, 0x300
	v_add_u32_e32 v14, s2, v188
	v_add_u32_e32 v15, s2, v189
	s_or_b32 s2, s1, 0x400
	v_add_u32_e32 v16, s2, v188
	v_add_u32_e32 v17, s2, v189
	s_or_b32 s2, s1, 0x500
	v_add_u32_e32 v18, s2, v188
	v_add_u32_e32 v19, s2, v189
	s_or_b32 s2, s1, 0x600
	v_add_u32_e32 v22, s2, v188
	v_add_u32_e32 v23, s2, v189
	s_or_b32 s2, s1, 0x700
	v_add_u32_e32 v24, s2, v188
	v_add_u32_e32 v25, s2, v189
	s_or_b32 s2, s1, 0x800
	v_add_u32_e32 v26, s2, v188
	v_add_u32_e32 v27, s2, v189
	s_or_b32 s2, s1, 0x900
	v_add_u32_e32 v28, s2, v188
	v_add_u32_e32 v29, s2, v189
	s_or_b32 s2, s1, 0xa00
	v_add_u32_e32 v70, s1, v184
	v_add_u32_e32 v6, s1, v188
	v_add_u32_e32 v7, s1, v189
	v_add_u32_e32 v32, s2, v188
	v_add_u32_e32 v33, s2, v189
	s_or_b32 s2, s1, 0xb00
	ds_read2st64_b32 v[2:3], v70 offset0:62 offset1:128
	ds_read2st64_b32 v[4:5], v70 offset0:129 offset1:130
	ds_read_b32 v10, v6
	ds_read_b32 v6, v7
	ds_read_b32 v11, v8
	ds_read_b32 v7, v9
	ds_read_b32 v12, v12
	ds_read_b32 v8, v13
	ds_read_b32 v13, v14
	ds_read_b32 v9, v15
	ds_read2st64_b32 v[14:15], v70 offset1:1
	ds_read2st64_b32 v[44:45], v70 offset0:2 offset1:3
	ds_read2st64_b32 v[46:47], v70 offset0:4 offset1:5
	ds_read2st64_b32 v[48:49], v70 offset0:6 offset1:7
	v_add_u32_e32 v34, s2, v188
	v_add_u32_e32 v35, s2, v189
	s_or_b32 s2, s1, 0xc00
	ds_read_b32 v20, v16
	ds_read_b32 v16, v17
	ds_read_b32 v21, v18
	ds_read_b32 v17, v19
	ds_read_b32 v22, v22
	ds_read_b32 v18, v23
	ds_read_b32 v23, v24
	ds_read_b32 v19, v25
	ds_read2st64_b32 v[24:25], v70 offset0:131 offset1:132
	ds_read2st64_b32 v[58:59], v70 offset0:133 offset1:134
	ds_read2st64_b32 v[56:57], v70 offset0:135 offset1:136
	ds_read2st64_b32 v[54:55], v70 offset0:137 offset1:138
	ds_read_b32 v30, v26
	ds_read_b32 v26, v27
	ds_read_b32 v31, v28
	ds_read_b32 v27, v29
	ds_read_b32 v32, v32
	ds_read_b32 v28, v33
	ds_read_b32 v33, v34
	ds_read_b32 v29, v35
	v_add_u32_e32 v34, s2, v188
	v_add_u32_e32 v35, s2, v189
	s_or_b32 s2, s1, 0xd00
	ds_read2st64_b32 v[50:51], v70 offset0:8 offset1:9
	ds_read2st64_b32 v[52:53], v70 offset0:10 offset1:11
	ds_read2st64_b32 v[60:61], v70 offset0:12 offset1:13
	ds_read2st64_b32 v[62:63], v70 offset0:14 offset1:15
	v_add_u32_e32 v37, s2, v188
	v_add_u32_e32 v38, s2, v189
	s_or_b32 s2, s1, 0xe00
	v_add_u32_e32 v39, s2, v188
	v_add_u32_e32 v41, s2, v189
	s_or_b32 s2, s1, 0xf00
	v_add_u32_e32 v42, s2, v188
	v_add_u32_e32 v43, s2, v189
	ds_read_b32 v36, v34
	ds_read_b32 v34, v35
	ds_read_b32 v37, v37
	ds_read_b32 v35, v38
	ds_read_b32 v40, v39
	ds_read_b32 v38, v41
	ds_read_b32 v41, v42
	ds_read_b32 v39, v43
	s_waitcnt lgkmcnt(14)
	v_pk_add_f32 v[42:43], v[14:15], 0 op_sel_hi:[1,0]
	v_pk_add_f32 v[66:67], v[48:49], 0 op_sel_hi:[1,0]
	s_waitcnt lgkmcnt(11)
	v_pk_add_f32 v[68:69], v[50:51], 0 op_sel_hi:[1,0]
	s_waitcnt lgkmcnt(9)
	v_pk_add_f32 v[50:51], v[60:61], 0 op_sel_hi:[1,0]
	ds_read2st64_b32 v[60:61], v70 offset0:141 offset1:142
	ds_read2st64_b32 v[14:15], v70 offset0:143 offset1:144
	ds_read2st64_b32 v[48:49], v70 offset0:145 offset1:146
	ds_read2st64_b32 v[72:73], v70 offset0:139 offset1:140
	v_pk_add_f32 v[64:65], v[46:47], 0 op_sel_hi:[1,0]
	s_waitcnt lgkmcnt(12)
	v_pk_add_f32 v[46:47], v[62:63], 0 op_sel_hi:[1,0]
	s_waitcnt lgkmcnt(3)
	v_mov_b32_e32 v62, v61
	s_waitcnt lgkmcnt(2)
	v_mov_b32_e32 v63, v14
	v_pk_add_f32 v[52:53], v[52:53], 0 op_sel_hi:[1,0]
	v_pk_add_f32 v[46:47], v[46:47], v[62:63]
	v_mov_b32_e32 v63, v60
	v_mov_b32_e32 v60, v55
	s_waitcnt lgkmcnt(0)
	v_mov_b32_e32 v61, v72
	v_pk_add_f32 v[52:53], v[52:53], v[60:61]
	v_mov_b32_e32 v60, v57
	v_mov_b32_e32 v61, v54
	v_pk_add_f32 v[54:55], v[68:69], v[60:61]
	v_mov_b32_e32 v60, v59
	v_mov_b32_e32 v61, v56
	v_pk_add_f32 v[56:57], v[66:67], v[60:61]
	v_mov_b32_e32 v60, v25
	v_mov_b32_e32 v61, v58
	v_pk_add_f32 v[44:45], v[44:45], 0 op_sel_hi:[1,0]
	v_pk_add_f32 v[58:59], v[64:65], v[60:61]
	v_mov_b32_e32 v60, v5
	v_mov_b32_e32 v61, v24
	v_pk_add_f32 v[24:25], v[44:45], v[60:61]
	v_mov_b32_e32 v44, v3
	v_mov_b32_e32 v45, v4
	v_mov_b32_e32 v62, v73
	v_pk_add_f32 v[4:5], v[42:43], v[44:45]
	v_pk_add_f32 v[50:51], v[50:51], v[62:63]
	v_pk_add_f32 v[4:5], v[4:5], v[10:11]
	v_pk_add_f32 v[10:11], v[24:25], v[12:13]
	v_pk_add_f32 v[24:25], v[52:53], v[32:33]
	v_pk_add_f32 v[32:33], v[46:47], v[40:41]
	s_or_b32 s2, s1, 0x1000
	v_pk_add_f32 v[12:13], v[58:59], v[20:21]
	v_pk_add_f32 v[20:21], v[56:57], v[22:23]
	v_pk_add_f32 v[22:23], v[54:55], v[30:31]
	v_pk_add_f32 v[30:31], v[50:51], v[36:37]
	v_pk_add_f32 v[46:47], v[32:33], v[38:39]
	v_pk_add_f32 v[32:33], v[4:5], v[6:7]
	v_add_u32_e32 v3, s2, v188
	v_add_u32_e32 v5, s2, v189
	s_or_b32 s2, s1, 0x1100
	v_pk_add_f32 v[44:45], v[30:31], v[34:35]
	v_pk_add_f32 v[34:35], v[10:11], v[8:9]
	v_add_u32_e32 v7, s2, v188
	v_add_u32_e32 v8, s2, v189
	s_or_b32 s2, s1, 0x1200
	v_add_u32_e32 v9, s2, v188
	v_add_u32_e32 v10, s2, v189
	s_or_b32 s2, s1, 0x1300
	v_pk_add_f32 v[36:37], v[12:13], v[16:17]
	v_add_u32_e32 v11, s2, v188
	v_add_u32_e32 v12, s2, v189
	s_or_b32 s2, s1, 0x1400
	ds_read2st64_b32 v[64:65], v70 offset0:56 offset1:57
	ds_read2st64_b32 v[66:67], v70 offset0:58 offset1:59
	ds_read2st64_b32 v[68:69], v70 offset0:60 offset1:61
	ds_read_b32 v4, v3
	ds_read_b32 v6, v5
	ds_read_b32 v5, v7
	ds_read_b32 v7, v8
	ds_read_b32 v8, v9
	ds_read_b32 v10, v10
	ds_read_b32 v9, v11
	ds_read_b32 v11, v12
	v_add_u32_e32 v3, s2, v188
	v_add_u32_e32 v14, s2, v189
	s_or_b32 s2, s1, 0x1500
	v_pk_add_f32 v[42:43], v[24:25], v[28:29]
; template <bool DIFF> ...
;     ...
;         have = wave < NM;
;         if (have) {
; #pragma unroll
;             for (int db = 0; db < 4; ++db)
; #pragma unroll
;                 for (int ii = 0; ii < 16; ++ii) { float a = 0.f;
; #pragma unroll
;                     for (int g = 0; g < NG; ++g) a += red[((g * NM + mp) * 64 + db * 16 + ii) * 64 + lane];
;                     O[db][ii] = a; }
	v_pk_add_f32 v[40:41], v[22:23], v[26:27]
	v_add_u32_e32 v23, s2, v188
	v_add_u32_e32 v24, s2, v189
	s_or_b32 s2, s1, 0x1600
	v_add_u32_e32 v25, s2, v188
	v_add_u32_e32 v26, s2, v189
	s_or_b32 s2, s1, 0x1700
	v_add_u32_e32 v27, s2, v188
	v_add_u32_e32 v28, s2, v189
	s_or_b32 s2, s1, 0x1800
	v_pk_add_f32 v[38:39], v[20:21], v[18:19]
	ds_read2st64_b32 v[12:13], v70 offset0:16 offset1:17
	ds_read2st64_b32 v[16:17], v70 offset0:18 offset1:19
	ds_read2st64_b32 v[18:19], v70 offset0:20 offset1:21
	ds_read2st64_b32 v[20:21], v70 offset0:22 offset1:23
	ds_read_b32 v22, v3
	ds_read_b32 v50, v14
	ds_read_b32 v23, v23
	ds_read_b32 v51, v24
	ds_read_b32 v24, v25
	ds_read_b32 v52, v26
	ds_read_b32 v25, v27
	ds_read_b32 v53, v28
	v_add_u32_e32 v3, s2, v188
	v_add_u32_e32 v14, s2, v189
	s_or_b32 s2, s1, 0x1900
	v_add_u32_e32 v57, s2, v188
	v_add_u32_e32 v59, s2, v189
	s_or_b32 s2, s1, 0x1a00
	v_add_u32_e32 v60, s2, v188
	v_add_u32_e32 v61, s2, v189
	s_or_b32 s2, s1, 0x1b00
	v_add_u32_e32 v63, s2, v188
	v_add_u32_e32 v71, s2, v189
	s_or_b32 s2, s1, 0x1c00
	ds_read2st64_b32 v[26:27], v70 offset0:147 offset1:148
	ds_read2st64_b32 v[28:29], v70 offset0:149 offset1:150
	ds_read2st64_b32 v[30:31], v70 offset0:151 offset1:152
	ds_read2st64_b32 v[54:55], v70 offset0:153 offset1:154
	ds_read_b32 v56, v3
	ds_read_b32 v58, v14
	ds_read_b32 v57, v57
	ds_read_b32 v59, v59
	ds_read_b32 v60, v60
	ds_read_b32 v62, v61
	ds_read_b32 v61, v63
	ds_read_b32 v63, v71
	v_add_u32_e32 v3, s2, v188
	v_add_u32_e32 v14, s2, v189
	s_or_b32 s2, s1, 0x1d00
	v_add_u32_e32 v71, s2, v188
	v_add_u32_e32 v83, s2, v189
	s_or_b32 s2, s1, 0x1e00
	v_add_u32_e32 v84, s2, v188
	v_add_u32_e32 v85, s2, v189
	s_or_b32 s2, s1, 0x1f00
	ds_read2st64_b32 v[72:73], v70 offset0:24 offset1:25
	ds_read2st64_b32 v[74:75], v70 offset0:26 offset1:27
	ds_read2st64_b32 v[76:77], v70 offset0:28 offset1:29
	ds_read2st64_b32 v[78:79], v70 offset0:30 offset1:31
	v_add_u32_e32 v87, s2, v188
	v_add_u32_e32 v88, s2, v189
	ds_read_b32 v80, v3
	ds_read_b32 v82, v14
	ds_read_b32 v81, v71
	ds_read_b32 v83, v83
	ds_read_b32 v84, v84
	ds_read_b32 v86, v85
	ds_read_b32 v85, v87
	ds_read_b32 v87, v88
	ds_read2st64_b32 v[88:89], v70 offset0:157 offset1:158
	ds_read2st64_b32 v[90:91], v70 offset0:159 offset1:160
	ds_read2st64_b32 v[92:93], v70 offset0:161 offset1:162
	ds_read2st64_b32 v[94:95], v70 offset0:155 offset1:156
	s_waitcnt lgkmcnt(12)
	v_pk_add_f32 v[78:79], v[78:79], 0 op_sel_hi:[1,0]
	s_waitcnt lgkmcnt(3)
	v_mov_b32_e32 v96, v89
	s_waitcnt lgkmcnt(2)
	v_mov_b32_e32 v97, v90
	v_pk_add_f32 v[74:75], v[74:75], 0 op_sel_hi:[1,0]
	v_pk_add_f32 v[78:79], v[78:79], v[96:97]
	v_mov_b32_e32 v97, v88
	v_mov_b32_e32 v88, v55
	s_waitcnt lgkmcnt(0)
	v_mov_b32_e32 v89, v94
	v_pk_add_f32 v[72:73], v[72:73], 0 op_sel_hi:[1,0]
	v_pk_add_f32 v[74:75], v[74:75], v[88:89]
	v_mov_b32_e32 v88, v31
	v_mov_b32_e32 v89, v54
	v_pk_add_f32 v[12:13], v[12:13], 0 op_sel_hi:[1,0]
	v_pk_add_f32 v[16:17], v[16:17], 0 op_sel_hi:[1,0]
	v_pk_add_f32 v[54:55], v[72:73], v[88:89]
	v_mov_b32_e32 v72, v29
	v_mov_b32_e32 v31, v28
	v_mov_b32_e32 v28, v49
	v_mov_b32_e32 v29, v26
	v_mov_b32_e32 v14, v15
	v_mov_b32_e32 v15, v48
	v_pk_add_f32 v[18:19], v[18:19], 0 op_sel_hi:[1,0]
	v_pk_add_f32 v[20:21], v[20:21], 0 op_sel_hi:[1,0]
	v_mov_b32_e32 v73, v30
	v_mov_b32_e32 v30, v27
	v_pk_add_f32 v[16:17], v[16:17], v[28:29]
	v_pk_add_f32 v[12:13], v[12:13], v[14:15]
	v_pk_add_f32 v[20:21], v[20:21], v[72:73]
	v_pk_add_f32 v[18:19], v[18:19], v[30:31]
	v_pk_add_f32 v[4:5], v[12:13], v[4:5]
	v_pk_add_f32 v[8:9], v[16:17], v[8:9]
	v_pk_add_f32 v[16:17], v[54:55], v[56:57]
	s_or_b32 s2, s1, 0x2000
	v_pk_add_f32 v[76:77], v[76:77], 0 op_sel_hi:[1,0]
	v_mov_b32_e32 v96, v95
	v_pk_add_f32 v[12:13], v[18:19], v[22:23]
	v_pk_add_f32 v[14:15], v[20:21], v[24:25]
	v_pk_add_f32 v[18:19], v[74:75], v[60:61]
	v_pk_add_f32 v[24:25], v[16:17], v[58:59]
	v_pk_add_f32 v[16:17], v[4:5], v[6:7]
	v_add_u32_e32 v3, s2, v188
	v_add_u32_e32 v5, s2, v189
	s_or_b32 s2, s1, 0x2100
	v_pk_add_f32 v[76:77], v[76:77], v[96:97]
	v_pk_add_f32 v[26:27], v[18:19], v[62:63]
	v_pk_add_f32 v[18:19], v[8:9], v[10:11]
	v_add_u32_e32 v7, s2, v188
	v_add_u32_e32 v8, s2, v189
	s_or_b32 s2, s1, 0x2200
	v_pk_add_f32 v[20:21], v[76:77], v[80:81]
	v_add_u32_e32 v9, s2, v188
	v_add_u32_e32 v10, s2, v189
	s_or_b32 s2, s1, 0x2300
	v_pk_add_f32 v[22:23], v[78:79], v[84:85]
	v_pk_add_f32 v[28:29], v[20:21], v[82:83]
	v_pk_add_f32 v[20:21], v[12:13], v[50:51]
	v_add_u32_e32 v11, s2, v188
	v_add_u32_e32 v12, s2, v189
	s_or_b32 s2, s1, 0x2400
	v_pk_add_f32 v[30:31], v[22:23], v[86:87]
	v_pk_add_f32 v[22:23], v[14:15], v[52:53]
	ds_read_b32 v4, v3
	ds_read_b32 v6, v5
	ds_read_b32 v5, v7
	ds_read_b32 v7, v8
	ds_read_b32 v8, v9
	ds_read_b32 v10, v10
	ds_read_b32 v9, v11
	ds_read_b32 v11, v12
	v_add_u32_e32 v3, s2, v188
	v_add_u32_e32 v53, s2, v189
	s_or_b32 s2, s1, 0x2500
	v_add_u32_e32 v54, s2, v188
	v_add_u32_e32 v55, s2, v189
	s_or_b32 s2, s1, 0x2600
	v_add_u32_e32 v56, s2, v188
	v_add_u32_e32 v57, s2, v189
	s_or_b32 s2, s1, 0x2700
	v_add_u32_e32 v58, s2, v188
	v_add_u32_e32 v59, s2, v189
	s_or_b32 s2, s1, 0x2800
	ds_read2st64_b32 v[12:13], v70 offset0:32 offset1:33
	ds_read2st64_b32 v[14:15], v70 offset0:34 offset1:35
	ds_read2st64_b32 v[48:49], v70 offset0:36 offset1:37
	ds_read2st64_b32 v[50:51], v70 offset0:38 offset1:39
	ds_read_b32 v52, v3
	ds_read_b32 v72, v53
	ds_read_b32 v53, v54
	ds_read_b32 v73, v55
	ds_read_b32 v54, v56
	ds_read_b32 v74, v57
	ds_read_b32 v55, v58
	ds_read_b32 v75, v59
	v_add_u32_e32 v3, s2, v188
	v_add_u32_e32 v71, s2, v189
	s_or_b32 s2, s1, 0x2900
	v_add_u32_e32 v77, s2, v188
; template <bool DIFF> ...
;     ...
;         have = wave < NM;
;         if (have) {
; #pragma unroll
;             for (int db = 0; db < 4; ++db)
; #pragma unroll
;                 for (int ii = 0; ii < 16; ++ii) { float a = 0.f;
; #pragma unroll
;                     for (int g = 0; g < NG; ++g) a += red[((g * NM + mp) * 64 + db * 16 + ii) * 64 + lane];
;                     O[db][ii] = a; }
	v_add_u32_e32 v79, s2, v189
	s_or_b32 s2, s1, 0x2a00
	v_add_u32_e32 v80, s2, v188
	v_add_u32_e32 v81, s2, v189
	s_or_b32 s2, s1, 0x2b00
	v_add_u32_e32 v83, s2, v188
	v_add_u32_e32 v84, s2, v189
	s_or_b32 s2, s1, 0x2c00
	ds_read2st64_b32 v[56:57], v70 offset0:163 offset1:164
	ds_read2st64_b32 v[58:59], v70 offset0:165 offset1:166
	ds_read2st64_b32 v[60:61], v70 offset0:167 offset1:168
	ds_read2st64_b32 v[62:63], v70 offset0:169 offset1:170
	ds_read_b32 v76, v3
	ds_read_b32 v78, v71
	ds_read_b32 v77, v77
	ds_read_b32 v79, v79
	ds_read_b32 v80, v80
	ds_read_b32 v82, v81
	ds_read_b32 v81, v83
	ds_read_b32 v83, v84
	v_add_u32_e32 v3, s2, v188
	v_add_u32_e32 v71, s2, v189
	s_or_b32 s2, s1, 0x2d00
	v_add_u32_e32 v90, s2, v188
	v_add_u32_e32 v99, s2, v189
	s_or_b32 s2, s1, 0x2e00
	v_add_u32_e32 v100, s2, v188
	v_add_u32_e32 v101, s2, v189
	s_or_b32 s2, s1, 0x2f00
	ds_read2st64_b32 v[84:85], v70 offset0:40 offset1:41
	ds_read2st64_b32 v[86:87], v70 offset0:42 offset1:43
	ds_read2st64_b32 v[88:89], v70 offset0:44 offset1:45
	ds_read2st64_b32 v[94:95], v70 offset0:46 offset1:47
	v_add_u32_e32 v103, s2, v188
	v_add_u32_e32 v104, s2, v189
	ds_read_b32 v96, v3
	ds_read_b32 v98, v71
	ds_read_b32 v97, v90
	ds_read_b32 v99, v99
	ds_read_b32 v100, v100
	ds_read_b32 v102, v101
	ds_read_b32 v101, v103
	ds_read_b32 v103, v104
	ds_read2st64_b32 v[104:105], v70 offset0:173 offset1:174
	ds_read2st64_b32 v[106:107], v70 offset0:175 offset1:176
	ds_read2st64_b32 v[108:109], v70 offset0:177 offset1:178
	ds_read2st64_b32 v[110:111], v70 offset0:171 offset1:172
	s_waitcnt lgkmcnt(12)
	v_pk_add_f32 v[94:95], v[94:95], 0 op_sel_hi:[1,0]
	s_waitcnt lgkmcnt(3)
	v_mov_b32_e32 v112, v105
	s_waitcnt lgkmcnt(2)
	v_mov_b32_e32 v113, v106
	v_pk_add_f32 v[86:87], v[86:87], 0 op_sel_hi:[1,0]
	v_pk_add_f32 v[94:95], v[94:95], v[112:113]
	v_mov_b32_e32 v113, v104
	v_mov_b32_e32 v104, v63
	s_waitcnt lgkmcnt(0)
	v_mov_b32_e32 v105, v110
	v_pk_add_f32 v[84:85], v[84:85], 0 op_sel_hi:[1,0]
	v_pk_add_f32 v[86:87], v[86:87], v[104:105]
	v_mov_b32_e32 v104, v61
	v_mov_b32_e32 v105, v62
	v_pk_add_f32 v[12:13], v[12:13], 0 op_sel_hi:[1,0]
	v_pk_add_f32 v[48:49], v[48:49], 0 op_sel_hi:[1,0]
	v_pk_add_f32 v[62:63], v[84:85], v[104:105]
	v_mov_b32_e32 v84, v59
	v_mov_b32_e32 v85, v60
	v_mov_b32_e32 v60, v57
	v_mov_b32_e32 v61, v58
	v_mov_b32_e32 v59, v56
	v_mov_b32_e32 v56, v91
	v_mov_b32_e32 v57, v92
	v_pk_add_f32 v[14:15], v[14:15], 0 op_sel_hi:[1,0]
	v_pk_add_f32 v[50:51], v[50:51], 0 op_sel_hi:[1,0]
	v_pk_add_f32 v[48:49], v[48:49], v[60:61]
	v_mov_b32_e32 v58, v93
	v_pk_add_f32 v[12:13], v[12:13], v[56:57]
	v_pk_add_f32 v[50:51], v[50:51], v[84:85]
	v_pk_add_f32 v[14:15], v[14:15], v[58:59]
	v_pk_add_f32 v[4:5], v[12:13], v[4:5]
	v_pk_add_f32 v[12:13], v[48:49], v[52:53]
	v_pk_add_f32 v[48:49], v[62:63], v[76:77]
	s_or_b32 s2, s1, 0x3000
	v_pk_add_f32 v[88:89], v[88:89], 0 op_sel_hi:[1,0]
	v_mov_b32_e32 v112, v111
	v_pk_add_f32 v[8:9], v[14:15], v[8:9]
	v_pk_add_f32 v[14:15], v[50:51], v[54:55]
	v_pk_add_f32 v[50:51], v[86:87], v[80:81]
	v_pk_add_f32 v[56:57], v[48:49], v[78:79]
	v_pk_add_f32 v[48:49], v[4:5], v[6:7]
	v_add_u32_e32 v3, s2, v188
	v_add_u32_e32 v5, s2, v189
	s_or_b32 s2, s1, 0x3100
	v_pk_add_f32 v[88:89], v[88:89], v[112:113]
	v_pk_add_f32 v[58:59], v[50:51], v[82:83]
	v_pk_add_f32 v[50:51], v[8:9], v[10:11]
	v_add_u32_e32 v7, s2, v188
	v_add_u32_e32 v8, s2, v189
	s_or_b32 s2, s1, 0x3200
	v_pk_add_f32 v[52:53], v[88:89], v[96:97]
	v_add_u32_e32 v9, s2, v188
	v_add_u32_e32 v10, s2, v189
	s_or_b32 s2, s1, 0x3300
	v_pk_add_f32 v[60:61], v[52:53], v[98:99]
	v_pk_add_f32 v[52:53], v[12:13], v[72:73]
	v_add_u32_e32 v11, s2, v188
	v_add_u32_e32 v12, s2, v189
	s_or_b32 s2, s1, 0x3400
	ds_read_b32 v4, v3
	ds_read_b32 v6, v5
	ds_read_b32 v5, v7
	ds_read_b32 v7, v8
	ds_read_b32 v8, v9
	ds_read_b32 v10, v10
	ds_read_b32 v9, v11
	ds_read_b32 v11, v12
	v_add_u32_e32 v3, s2, v188
	v_add_u32_e32 v71, s2, v189
	s_or_b32 s2, s1, 0x3500
	v_add_u32_e32 v77, s2, v188
	v_add_u32_e32 v78, s2, v189
	s_or_b32 s2, s1, 0x3600
	v_add_u32_e32 v79, s2, v188
	v_add_u32_e32 v82, s2, v189
	s_or_b32 s2, s1, 0x3700
	v_pk_add_f32 v[54:55], v[94:95], v[100:101]
	v_add_u32_e32 v83, s2, v188
	v_add_u32_e32 v84, s2, v189
	s_or_b32 s2, s1, 0x3800
	v_pk_add_f32 v[62:63], v[54:55], v[102:103]
	v_pk_add_f32 v[54:55], v[14:15], v[74:75]
	ds_read2st64_b32 v[12:13], v70 offset0:48 offset1:49
	ds_read2st64_b32 v[14:15], v70 offset0:50 offset1:51
	ds_read2st64_b32 v[72:73], v70 offset0:52 offset1:53
	ds_read2st64_b32 v[74:75], v70 offset0:54 offset1:55
	ds_read_b32 v76, v3
	ds_read_b32 v80, v71
	ds_read_b32 v77, v77
	ds_read_b32 v81, v78
	ds_read_b32 v78, v79
	ds_read_b32 v82, v82
	ds_read_b32 v79, v83
	ds_read_b32 v83, v84
	v_add_u32_e32 v3, s2, v188
	v_add_u32_e32 v71, s2, v189
	s_or_b32 s2, s1, 0x3900
	v_add_u32_e32 v93, s2, v188
	v_add_u32_e32 v95, s2, v189
	s_or_b32 s2, s1, 0x3a00
	v_add_u32_e32 v96, s2, v188
	v_add_u32_e32 v97, s2, v189
	s_or_b32 s2, s1, 0x3b00
	s_or_b32 s0, s0, 0x3f00
	v_add_u32_e32 v99, s2, v188
	v_add_u32_e32 v100, s2, v189
	v_add_u32_e32 v102, s0, v184
	ds_read2st64_b32 v[84:85], v70 offset0:179 offset1:180
	ds_read2st64_b32 v[86:87], v70 offset0:181 offset1:182
	ds_read2st64_b32 v[88:89], v70 offset0:183 offset1:184
	ds_read2st64_b32 v[90:91], v70 offset0:185 offset1:186
	ds_read_b32 v92, v3
	ds_read_b32 v94, v71
	ds_read_b32 v93, v93
	ds_read_b32 v95, v95
	ds_read_b32 v96, v96
	ds_read_b32 v98, v97
	ds_read_b32 v97, v99
	ds_read_b32 v99, v100
	ds_read2st64_b32 v[100:101], v70 offset0:187 offset1:188
	ds_read2st64_b32 v[70:71], v70 offset0:189 offset1:190
	ds_read2st64_b32 v[102:103], v102 offset1:128
	s_or_b32 s2, s1, 0x3c00
	v_add_u32_e32 v3, s2, v188
	v_add_u32_e32 v105, s2, v189
	s_or_b32 s2, s1, 0x3d00
	s_or_b32 s1, s1, 0x3e00
	v_add_u32_e32 v111, s2, v189
	v_add_u32_e32 v112, s1, v188
	v_add_u32_e32 v113, s1, v189
	v_add_u32_e32 v115, s0, v188
	v_add_u32_e32 v106, s2, v188
	v_add_u32_e32 v116, s0, v189
	ds_read_b32 v104, v3
	ds_read_b32 v110, v105
	ds_read_b32 v105, v106
	ds_read_b32 v111, v111
	ds_read_b32 v112, v112
	ds_read_b32 v114, v113
	ds_read_b32 v113, v115
	ds_read_b32 v115, v116
	s_waitcnt lgkmcnt(8)
; template <bool DIFF> ...
;     ...
; #pragma unroll
;             for (int db = 0; db < 4; ++db)
; #pragma unroll
;                 for (int ii = 0; ii < 16; ++ii) { float a = 0.f;
; #pragma unroll
;                     for (int g = 0; g < NG; ++g) a += red[((g * NM + mp) * 64 + db * 16 + ii) * 64 + lane];
;                     O[db][ii] = a; }
;             float lt = 0.f;
; #pragma unroll
;             for (int g = 0; g < NG; ++g) lt += lb[(g * NM + mp) * 32 + r];
;             l_ = lt;
	v_mov_b32_e32 v3, v102
	v_pk_add_f32 v[2:3], v[2:3], 0 op_sel_hi:[1,0]
	v_mov_b32_e32 v102, v71
	v_pk_add_f32 v[66:67], v[66:67], 0 op_sel_hi:[1,0]
	v_pk_add_f32 v[2:3], v[2:3], v[102:103]
	v_mov_b32_e32 v103, v70
	v_mov_b32_e32 v70, v91
	v_mov_b32_e32 v71, v100
	v_pk_add_f32 v[64:65], v[64:65], 0 op_sel_hi:[1,0]
	v_pk_add_f32 v[66:67], v[66:67], v[70:71]
	v_mov_b32_e32 v70, v89
	v_mov_b32_e32 v71, v90
	v_pk_add_f32 v[74:75], v[74:75], 0 op_sel_hi:[1,0]
	v_pk_add_f32 v[64:65], v[64:65], v[70:71]
	v_mov_b32_e32 v70, v87
	v_mov_b32_e32 v71, v88
	v_pk_add_f32 v[72:73], v[72:73], 0 op_sel_hi:[1,0]
	v_pk_add_f32 v[70:71], v[74:75], v[70:71]
	v_mov_b32_e32 v74, v85
	v_mov_b32_e32 v75, v86
	v_pk_add_f32 v[14:15], v[14:15], 0 op_sel_hi:[1,0]
	v_pk_add_f32 v[72:73], v[72:73], v[74:75]
	v_mov_b32_e32 v74, v109
	v_mov_b32_e32 v75, v84
	v_pk_add_f32 v[12:13], v[12:13], 0 op_sel_hi:[1,0]
	v_pk_add_f32 v[68:69], v[68:69], 0 op_sel_hi:[1,0]
	v_mov_b32_e32 v102, v101
	v_pk_add_f32 v[14:15], v[14:15], v[74:75]
	v_mov_b32_e32 v74, v107
	v_mov_b32_e32 v75, v108
	s_waitcnt lgkmcnt(1)
	v_pk_add_f32 v[2:3], v[2:3], v[112:113]
	v_pk_add_f32 v[68:69], v[68:69], v[102:103]
	v_pk_add_f32 v[12:13], v[12:13], v[74:75]
	v_pk_add_f32 v[8:9], v[14:15], v[8:9]
	v_pk_add_f32 v[14:15], v[70:71], v[78:79]
	s_waitcnt lgkmcnt(0)
	v_pk_add_f32 v[78:79], v[2:3], v[114:115]
	ds_read2st64_b32 v[2:3], v0 offset1:1
	v_pk_add_f32 v[4:5], v[12:13], v[4:5]
	v_pk_add_f32 v[12:13], v[72:73], v[76:77]
	v_pk_add_f32 v[68:69], v[68:69], v[104:105]
	v_pk_add_f32 v[64:65], v[64:65], v[92:93]
	v_pk_add_f32 v[76:77], v[68:69], v[110:111]
	v_pk_add_f32 v[68:69], v[12:13], v[80:81]
	ds_read2st64_b32 v[12:13], v0 offset0:2 offset1:3
	s_waitcnt lgkmcnt(1)
	v_add_f32_e32 v0, 0, v2
	v_add_f32_e32 v0, v0, v3
	v_pk_add_f32 v[66:67], v[66:67], v[96:97]
	v_pk_add_f32 v[72:73], v[64:65], v[94:95]
	s_waitcnt lgkmcnt(0)
	v_add_f32_e32 v0, v0, v12
	v_pk_add_f32 v[74:75], v[66:67], v[98:99]
	v_pk_add_f32 v[70:71], v[14:15], v[82:83]
	v_pk_add_f32 v[66:67], v[8:9], v[10:11]
	v_pk_add_f32 v[64:65], v[4:5], v[6:7]
	v_add_f32_e32 v80, v0, v13
